# GEMM K-loop heads pinned to 64-byte boundaries (placement made independent of other edits)
# speedup vs baseline: 1.0020x; 1.0020x over previous
;     __device__ bool next(int i, Unit& u) const { const int L = i * G + c; if (L >= 192) return false; u.pm = L / 6; u.pn = L % 6; return true; }
;     __device__ __forceinline__ size_t a_extra(const Unit& u) const { return (size_t)(u.pn >> 1) * ((size_t)T * 512 * 2); }
;     __device__ bool next(int i, Unit& u) const { const int L = i * G + c; if (L >= 256) return false; u.pm = L >> 3; u.pn = L & 7; return true; }
;     __device__ __forceinline__ size_t a_extra(const Unit& u) const { return (size_t)(u.pn >> 1) * 512 * 2; }
;     __device__ __forceinline__ size_t b_extra(const Unit& u) const { return (size_t)(u.pn >> 1) * 512 * 2 - (size_t)(u.pn & ~1) * ((size_t)256 * D * 2); }
; template <class Epi, class Sched, bool ALIGN_EPI = true, bool SP2 = true, bool GS = false>
; __device__ __forceinline__ void gemm_phase(PG8_LAS unsigned char* lds, const Gemm g, const Sched& S, const Epi& E, const float* gs_ss = nullptr) {
;     ...
;         const bool has_next = S.next(ui + 1, nxt);
;         const char* nA = has_next ? (const char*)g.A + S.a_extra(nxt) + (size_t)nxt.pm * tstep : cA; const char* nB = has_next ? (const char*)g.Bt + S.b_extra(nxt) + (size_t)nxt.pn * tstep : cB;
;         for (int t = 0; t < nt; t += 2) {
;             const bool last = (t == nt - 2);
;             const char* a1 = cA + (size_t)(t + 1) * kstep;
;             const char* a2 = last ? nA : cA + (size_t)(t + 2) * kstep; const char* b2 = last ? nB : cB + (size_t)(t + 2) * kstep;
;             const char* a3 = a2 + kstep; const char* b3 = b2 + kstep;
;     ...
; #pragma unroll
;         for (int a = 0; a < 2; ++a)
; #pragma unroll
;             for (int b = 0; b < 2; ++b)
; #pragma unroll
;                 for (int m = 0; m < 4; ++m)
; #pragma unroll
;                     for (int n = 0; n < 2; ++n) acc[a][b][m][n] = (f32x4){0.f, 0.f, 0.f, 0.f};
;         cur = nxt; cA = nA; cB = nB; ++ui;
.LBB0_150:
	s_ashr_i32 s53, s52, 31
	s_lshl_b64 s[2:3], s[52:53], 20
	s_add_u32 s54, s16, s2
	s_addc_u32 s55, s17, s3
	s_and_b64 s[2:3], s[38:39], exec
	s_cselect_b32 s13, s55, s41
	s_cselect_b32 s53, s54, s40
	s_ashr_i32 s51, s50, 31
	s_lshl_b64 s[2:3], s[50:51], 20
	s_add_u32 s56, s18, s2
	s_addc_u32 s57, s22, s3
	s_and_b64 s[2:3], s[38:39], exec
	s_cselect_b32 s51, s57, s43
	s_cselect_b32 s64, s56, s42
	s_add_u32 s40, s40, 0x80080
	s_addc_u32 s41, s41, 0
	s_add_u32 s42, s42, 0x100
	v_mov_b32_e32 v2, 0
	s_addc_u32 s43, s43, 0
	s_mov_b32 s65, -2
	v_mov_b32_e32 v3, v2
	v_mov_b32_e32 v4, v2
	v_mov_b32_e32 v5, v2
	v_mov_b32_e32 v6, v2
	v_mov_b32_e32 v7, v2
	v_mov_b32_e32 v8, v2
	v_mov_b32_e32 v9, v2
	v_mov_b32_e32 v18, v2
	v_mov_b32_e32 v19, v2
	v_mov_b32_e32 v20, v2
	v_mov_b32_e32 v21, v2
	v_mov_b32_e32 v22, v2
	v_mov_b32_e32 v23, v2
	v_mov_b32_e32 v24, v2
	v_mov_b32_e32 v25, v2
	v_mov_b32_e32 v34, v2
	v_mov_b32_e32 v35, v2
	v_mov_b32_e32 v36, v2
	v_mov_b32_e32 v37, v2
	v_mov_b32_e32 v38, v2
	v_mov_b32_e32 v39, v2
	v_mov_b32_e32 v40, v2
	v_mov_b32_e32 v41, v2
	v_mov_b32_e32 v50, v2
	v_mov_b32_e32 v51, v2
	v_mov_b32_e32 v52, v2
	v_mov_b32_e32 v53, v2
	v_mov_b32_e32 v54, v2
	v_mov_b32_e32 v55, v2
	v_mov_b32_e32 v56, v2
	v_mov_b32_e32 v57, v2
	v_mov_b32_e32 v10, v2
	v_mov_b32_e32 v11, v2
	v_mov_b32_e32 v12, v2
	v_mov_b32_e32 v13, v2
	v_mov_b32_e32 v14, v2
	v_mov_b32_e32 v15, v2
	v_mov_b32_e32 v16, v2
	v_mov_b32_e32 v17, v2
	v_mov_b32_e32 v26, v2
	v_mov_b32_e32 v27, v2
	v_mov_b32_e32 v28, v2
	v_mov_b32_e32 v29, v2
	v_mov_b32_e32 v30, v2
	v_mov_b32_e32 v31, v2
	v_mov_b32_e32 v32, v2
	v_mov_b32_e32 v33, v2
	v_mov_b32_e32 v42, v2
	v_mov_b32_e32 v43, v2
	v_mov_b32_e32 v44, v2
	v_mov_b32_e32 v45, v2
	v_mov_b32_e32 v46, v2
	v_mov_b32_e32 v47, v2
	v_mov_b32_e32 v48, v2
	v_mov_b32_e32 v49, v2
	v_mov_b32_e32 v58, v2
	v_mov_b32_e32 v59, v2
	v_mov_b32_e32 v60, v2
	v_mov_b32_e32 v61, v2
	v_mov_b32_e32 v62, v2
	v_mov_b32_e32 v63, v2
	v_mov_b32_e32 v64, v2
	v_mov_b32_e32 v65, v2
	v_mov_b32_e32 v66, v2
	v_mov_b32_e32 v67, v2
	v_mov_b32_e32 v68, v2
	v_mov_b32_e32 v69, v2
	v_mov_b32_e32 v70, v2
	v_mov_b32_e32 v71, v2
	v_mov_b32_e32 v72, v2
	v_mov_b32_e32 v73, v2
	v_mov_b32_e32 v82, v2
	v_mov_b32_e32 v83, v2
	v_mov_b32_e32 v84, v2
	v_mov_b32_e32 v85, v2
	v_mov_b32_e32 v86, v2
	v_mov_b32_e32 v87, v2
	v_mov_b32_e32 v88, v2
	v_mov_b32_e32 v89, v2
	v_mov_b32_e32 v98, v2
	v_mov_b32_e32 v99, v2
	v_mov_b32_e32 v100, v2
	v_mov_b32_e32 v101, v2
	v_mov_b32_e32 v102, v2
	v_mov_b32_e32 v103, v2
	v_mov_b32_e32 v104, v2
	v_mov_b32_e32 v105, v2
	v_mov_b32_e32 v114, v2
	v_mov_b32_e32 v115, v2
	v_mov_b32_e32 v116, v2
	v_mov_b32_e32 v117, v2
	v_mov_b32_e32 v118, v2
	v_mov_b32_e32 v119, v2
	v_mov_b32_e32 v120, v2
	v_mov_b32_e32 v121, v2
	v_mov_b32_e32 v74, v2
	v_mov_b32_e32 v75, v2
	v_mov_b32_e32 v76, v2
	v_mov_b32_e32 v77, v2
	v_mov_b32_e32 v78, v2
	v_mov_b32_e32 v79, v2
	v_mov_b32_e32 v80, v2
	v_mov_b32_e32 v81, v2
	v_mov_b32_e32 v90, v2
	v_mov_b32_e32 v91, v2
	v_mov_b32_e32 v92, v2
	v_mov_b32_e32 v93, v2
	v_mov_b32_e32 v94, v2
	v_mov_b32_e32 v95, v2
	v_mov_b32_e32 v96, v2
	v_mov_b32_e32 v97, v2
	v_mov_b32_e32 v106, v2
	v_mov_b32_e32 v107, v2
	v_mov_b32_e32 v108, v2
	v_mov_b32_e32 v109, v2
	v_mov_b32_e32 v110, v2
	v_mov_b32_e32 v111, v2
	v_mov_b32_e32 v112, v2
	v_mov_b32_e32 v113, v2
	v_mov_b32_e32 v122, v2
	v_mov_b32_e32 v123, v2
	v_mov_b32_e32 v124, v2
	v_mov_b32_e32 v125, v2
	v_mov_b32_e32 v126, v2
	v_mov_b32_e32 v127, v2
	v_mov_b32_e32 v128, v2
	v_mov_b32_e32 v129, v2
	.p2align	6

;     __device__ bool next(int i, Unit& u) const { const int L = i * G + c; if (L >= 192) return false; u.pm = L / 6; u.pn = L % 6; return true; }
;     __device__ bool next(int i, Unit& u) const { const int L = i * G + c; if (L >= 256) return false; u.pm = L >> 3; u.pn = L & 7; return true; }
;     __device__ bool next(int i, Unit& u) const {
;         if (so.next(i, u)) return true;
;         const int L = i * so.G + so.c - so.nwg; if (L >= 64) return false;
;         u.pm = L & 3; u.pn = 14 + (L >> 2); return true;
;     }
; template <class Epi, class Sched, bool ALIGN_EPI = true, bool SP2 = true, bool GS = false>
; __device__ __forceinline__ void gemm_phase(PG8_LAS unsigned char* lds, const Gemm g, const Sched& S, const Epi& E, const float* gs_ss = nullptr) {
;     ...
; #pragma unroll
;         for (int a = 0; a < 2; ++a)
; #pragma unroll
;             for (int b = 0; b < 2; ++b)
; #pragma unroll
;                 for (int m = 0; m < 4; ++m)
; #pragma unroll
;                     for (int n = 0; n < 2; ++n) acc[a][b][m][n] = (f32x4){0.f, 0.f, 0.f, 0.f};
;         cur = nxt; cA = nA; cB = nB; ++ui;
.LBB0_313:
	s_ashr_i32 s51, s50, 31
	s_lshl_b64 s[2:3], s[50:51], 20
	s_cmp_gt_i32 s48, 13
	s_cselect_b32 s13, 0xd8c0000, 0
	s_cselect_b32 s17, 0x5200000, 0
	s_add_u32 s13, s18, s13
	s_addc_u32 s16, s22, 0
	s_add_u32 s54, s13, s2
	s_addc_u32 s55, s16, s3
	s_and_b64 s[2:3], s[52:53], exec
	s_cselect_b32 s13, s55, s39
	s_cselect_b32 s16, s54, s38
	s_add_u32 s17, s8, s17
	s_addc_u32 s20, s9, 0
	s_ashr_i32 s49, s48, 31
	s_lshl_b64 s[2:3], s[48:49], 20
	s_add_u32 s56, s17, s2
	s_addc_u32 s57, s20, s3
	s_and_b64 s[2:3], s[52:53], exec
	s_cselect_b32 s17, s57, s41
	s_cselect_b32 s49, s56, s40
	s_add_u32 s38, s38, 0x80080
	s_addc_u32 s39, s39, 0
	s_add_u32 s40, s40, 0x100
	v_mov_b32_e32 v2, 0
	s_addc_u32 s41, s41, 0
	s_mov_b32 s51, -2
	v_mov_b32_e32 v3, v2
	v_mov_b32_e32 v4, v2
	v_mov_b32_e32 v5, v2
	v_mov_b32_e32 v6, v2
	v_mov_b32_e32 v7, v2
	v_mov_b32_e32 v8, v2
	v_mov_b32_e32 v9, v2
	v_mov_b32_e32 v10, v2
	v_mov_b32_e32 v11, v2
	v_mov_b32_e32 v12, v2
	v_mov_b32_e32 v13, v2
	v_mov_b32_e32 v18, v2
	v_mov_b32_e32 v19, v2
	v_mov_b32_e32 v20, v2
	v_mov_b32_e32 v21, v2
	v_mov_b32_e32 v26, v2
	v_mov_b32_e32 v27, v2
	v_mov_b32_e32 v28, v2
	v_mov_b32_e32 v29, v2
	v_mov_b32_e32 v34, v2
	v_mov_b32_e32 v35, v2
	v_mov_b32_e32 v36, v2
	v_mov_b32_e32 v37, v2
	v_mov_b32_e32 v42, v2
	v_mov_b32_e32 v43, v2
	v_mov_b32_e32 v44, v2
	v_mov_b32_e32 v45, v2
	v_mov_b32_e32 v50, v2
	v_mov_b32_e32 v51, v2
	v_mov_b32_e32 v52, v2
	v_mov_b32_e32 v53, v2
	v_mov_b32_e32 v14, v2
	v_mov_b32_e32 v15, v2
	v_mov_b32_e32 v16, v2
	v_mov_b32_e32 v17, v2
	v_mov_b32_e32 v22, v2
	v_mov_b32_e32 v23, v2
	v_mov_b32_e32 v24, v2
	v_mov_b32_e32 v25, v2
	v_mov_b32_e32 v30, v2
	v_mov_b32_e32 v31, v2
	v_mov_b32_e32 v32, v2
	v_mov_b32_e32 v33, v2
	v_mov_b32_e32 v38, v2
	v_mov_b32_e32 v39, v2
	v_mov_b32_e32 v40, v2
	v_mov_b32_e32 v41, v2
	v_mov_b32_e32 v46, v2
	v_mov_b32_e32 v47, v2
	v_mov_b32_e32 v48, v2
	v_mov_b32_e32 v49, v2
	v_mov_b32_e32 v54, v2
	v_mov_b32_e32 v55, v2
	v_mov_b32_e32 v56, v2
	v_mov_b32_e32 v57, v2
	v_mov_b32_e32 v58, v2
	v_mov_b32_e32 v59, v2
	v_mov_b32_e32 v60, v2
	v_mov_b32_e32 v61, v2
	v_mov_b32_e32 v62, v2
	v_mov_b32_e32 v63, v2
	v_mov_b32_e32 v64, v2
	v_mov_b32_e32 v65, v2
	v_mov_b32_e32 v66, v2
	v_mov_b32_e32 v67, v2
	v_mov_b32_e32 v68, v2
	v_mov_b32_e32 v69, v2
	v_mov_b32_e32 v70, v2
	v_mov_b32_e32 v71, v2
	v_mov_b32_e32 v72, v2
	v_mov_b32_e32 v73, v2
	v_mov_b32_e32 v74, v2
	v_mov_b32_e32 v75, v2
	v_mov_b32_e32 v76, v2
	v_mov_b32_e32 v77, v2
	v_mov_b32_e32 v82, v2
	v_mov_b32_e32 v83, v2
	v_mov_b32_e32 v84, v2
	v_mov_b32_e32 v85, v2
	v_mov_b32_e32 v90, v2
	v_mov_b32_e32 v91, v2
	v_mov_b32_e32 v92, v2
	v_mov_b32_e32 v93, v2
	v_mov_b32_e32 v98, v2
	v_mov_b32_e32 v99, v2
	v_mov_b32_e32 v100, v2
	v_mov_b32_e32 v101, v2
	v_mov_b32_e32 v106, v2
	v_mov_b32_e32 v107, v2
	v_mov_b32_e32 v108, v2
	v_mov_b32_e32 v109, v2
	v_mov_b32_e32 v114, v2
	v_mov_b32_e32 v115, v2
	v_mov_b32_e32 v116, v2
	v_mov_b32_e32 v117, v2
	v_mov_b32_e32 v78, v2
	v_mov_b32_e32 v79, v2
	v_mov_b32_e32 v80, v2
	v_mov_b32_e32 v81, v2
	v_mov_b32_e32 v86, v2
	v_mov_b32_e32 v87, v2
	v_mov_b32_e32 v88, v2
	v_mov_b32_e32 v89, v2
	v_mov_b32_e32 v94, v2
	v_mov_b32_e32 v95, v2
	v_mov_b32_e32 v96, v2
	v_mov_b32_e32 v97, v2
	v_mov_b32_e32 v102, v2
	v_mov_b32_e32 v103, v2
	v_mov_b32_e32 v104, v2
	v_mov_b32_e32 v105, v2
	v_mov_b32_e32 v110, v2
	v_mov_b32_e32 v111, v2
	v_mov_b32_e32 v112, v2
	v_mov_b32_e32 v113, v2
	v_mov_b32_e32 v118, v2
	v_mov_b32_e32 v119, v2
	v_mov_b32_e32 v120, v2
	v_mov_b32_e32 v121, v2
	v_mov_b32_e32 v122, v2
	v_mov_b32_e32 v123, v2
	v_mov_b32_e32 v124, v2
	v_mov_b32_e32 v125, v2
	v_mov_b32_e32 v126, v2
	v_mov_b32_e32 v127, v2
	v_mov_b32_e32 v128, v2
	v_mov_b32_e32 v129, v2
	.p2align	6

;     __device__ __forceinline__ size_t a_extra(const Unit& u) const { return (size_t)(u.pn >> 1) * 512 * 2; }
;     __device__ __forceinline__ size_t a_extra(const Unit& u) const { return (size_t)(u.pn >> 1) * ((size_t)T * 512 * 2); }
; template <class Epi, class Sched, bool ALIGN_EPI = true, bool SP2 = true, bool GS = false>
; __device__ __forceinline__ void gemm_phase(PG8_LAS unsigned char* lds, const Gemm g, const Sched& S, const Epi& E, const float* gs_ss = nullptr) {
;     ...
; #pragma unroll
;         for (int a = 0; a < 2; ++a)
; #pragma unroll
;             for (int b = 0; b < 2; ++b)
; #pragma unroll
;                 for (int m = 0; m < 4; ++m)
; #pragma unroll
;                     for (int n = 0; n < 2; ++n) acc[a][b][m][n] = (f32x4){0.f, 0.f, 0.f, 0.f};
;         cur = nxt; cA = nA; cB = nB; ++ui;
.LBB0_787:
	s_ashr_i32 s8, s12, 1
	s_ashr_i32 s9, s8, 31
	s_lshl_b64 s[8:9], s[8:9], 23
	s_add_u32 s13, s44, s8
	s_addc_u32 s16, s45, s9
	s_ashr_i32 s57, s56, 31
	s_lshl_b64 s[8:9], s[56:57], 18
	s_add_u32 s60, s13, s8
	s_addc_u32 s61, s16, s9
	s_and_b64 s[8:9], s[62:63], exec
	s_cselect_b32 s16, s61, s3
	s_cselect_b32 s17, s60, s2
	s_ashr_i32 s13, s12, 31
	s_lshl_b64 s[8:9], s[12:13], 18
	s_add_u32 s8, s23, s8
	s_addc_u32 s9, s24, s9
	s_and_b64 s[20:21], s[62:63], exec
	s_cselect_b32 s13, s9, s41
	s_cselect_b32 s18, s8, s40
	s_add_u32 s34, s2, 0x20080
	s_addc_u32 s35, s3, 0
	s_add_u32 s29, s40, 0x100
	s_waitcnt lgkmcnt(0)
	v_mov_b32_e32 v2, 0
	s_addc_u32 s40, s41, 0
	s_mov_b32 s41, -2
	v_mov_b32_e32 v3, v2
	v_mov_b32_e32 v4, v2
	v_mov_b32_e32 v5, v2
	v_mov_b32_e32 v6, v2
	v_mov_b32_e32 v7, v2
	v_mov_b32_e32 v8, v2
	v_mov_b32_e32 v9, v2
	v_mov_b32_e32 v22, v2
	v_mov_b32_e32 v23, v2
	v_mov_b32_e32 v24, v2
	v_mov_b32_e32 v25, v2
	v_mov_b32_e32 v34, v2
	v_mov_b32_e32 v35, v2
	v_mov_b32_e32 v36, v2
	v_mov_b32_e32 v37, v2
	v_mov_b32_e32 v62, v2
	v_mov_b32_e32 v63, v2
	v_mov_b32_e32 v64, v2
	v_mov_b32_e32 v65, v2
	v_mov_b32_e32 v66, v2
	v_mov_b32_e32 v67, v2
	v_mov_b32_e32 v68, v2
	v_mov_b32_e32 v69, v2
	v_mov_b32_e32 v86, v2
	v_mov_b32_e32 v87, v2
	v_mov_b32_e32 v88, v2
	v_mov_b32_e32 v89, v2
	v_mov_b32_e32 v90, v2
	v_mov_b32_e32 v91, v2
	v_mov_b32_e32 v92, v2
	v_mov_b32_e32 v93, v2
	v_mov_b32_e32 v10, v2
	v_mov_b32_e32 v11, v2
	v_mov_b32_e32 v12, v2
	v_mov_b32_e32 v13, v2
	v_mov_b32_e32 v14, v2
	v_mov_b32_e32 v15, v2
	v_mov_b32_e32 v16, v2
	v_mov_b32_e32 v17, v2
	v_mov_b32_e32 v50, v2
	v_mov_b32_e32 v51, v2
	v_mov_b32_e32 v52, v2
	v_mov_b32_e32 v53, v2
	v_mov_b32_e32 v54, v2
	v_mov_b32_e32 v55, v2
	v_mov_b32_e32 v56, v2
	v_mov_b32_e32 v57, v2
	v_mov_b32_e32 v74, v2
	v_mov_b32_e32 v75, v2
	v_mov_b32_e32 v76, v2
	v_mov_b32_e32 v77, v2
	v_mov_b32_e32 v78, v2
	v_mov_b32_e32 v79, v2
	v_mov_b32_e32 v80, v2
	v_mov_b32_e32 v81, v2
	v_mov_b32_e32 v98, v2
	v_mov_b32_e32 v99, v2
	v_mov_b32_e32 v100, v2
	v_mov_b32_e32 v101, v2
	v_mov_b32_e32 v102, v2
	v_mov_b32_e32 v103, v2
	v_mov_b32_e32 v104, v2
	v_mov_b32_e32 v105, v2
	v_mov_b32_e32 v110, v2
	v_mov_b32_e32 v111, v2
	v_mov_b32_e32 v112, v2
	v_mov_b32_e32 v113, v2
	v_mov_b32_e32 v114, v2
	v_mov_b32_e32 v115, v2
	v_mov_b32_e32 v116, v2
	v_mov_b32_e32 v117, v2
	v_mov_b32_e32 v130, v2
	v_mov_b32_e32 v131, v2
	v_mov_b32_e32 v132, v2
	v_mov_b32_e32 v133, v2
	v_mov_b32_e32 v134, v2
	v_mov_b32_e32 v135, v2
	v_mov_b32_e32 v136, v2
	v_mov_b32_e32 v137, v2
	v_mov_b32_e32 v146, v2
	v_mov_b32_e32 v147, v2
	v_mov_b32_e32 v148, v2
	v_mov_b32_e32 v149, v2
	v_mov_b32_e32 v150, v2
	v_mov_b32_e32 v151, v2
	v_mov_b32_e32 v152, v2
	v_mov_b32_e32 v153, v2
	v_mov_b32_e32 v162, v2
	v_mov_b32_e32 v163, v2
	v_mov_b32_e32 v164, v2
	v_mov_b32_e32 v165, v2
	v_mov_b32_e32 v166, v2
	v_mov_b32_e32 v167, v2
	v_mov_b32_e32 v168, v2
	v_mov_b32_e32 v169, v2
	v_mov_b32_e32 v122, v2
	v_mov_b32_e32 v123, v2
	v_mov_b32_e32 v124, v2
	v_mov_b32_e32 v125, v2
	v_mov_b32_e32 v126, v2
	v_mov_b32_e32 v127, v2
	v_mov_b32_e32 v128, v2
	v_mov_b32_e32 v129, v2
	v_mov_b32_e32 v138, v2
	v_mov_b32_e32 v139, v2
	v_mov_b32_e32 v140, v2
	v_mov_b32_e32 v141, v2
	v_mov_b32_e32 v142, v2
	v_mov_b32_e32 v143, v2
	v_mov_b32_e32 v144, v2
	v_mov_b32_e32 v145, v2
	v_mov_b32_e32 v154, v2
	v_mov_b32_e32 v155, v2
	v_mov_b32_e32 v156, v2
	v_mov_b32_e32 v157, v2
	v_mov_b32_e32 v158, v2
	v_mov_b32_e32 v159, v2
	v_mov_b32_e32 v160, v2
	v_mov_b32_e32 v161, v2
	v_mov_b32_e32 v170, v2
	v_mov_b32_e32 v171, v2
	v_mov_b32_e32 v172, v2
	v_mov_b32_e32 v173, v2
	v_mov_b32_e32 v174, v2
	v_mov_b32_e32 v175, v2
	v_mov_b32_e32 v176, v2
	v_mov_b32_e32 v177, v2
	.p2align	6

; template <class Epi, class Sched, bool ALIGN_EPI = true, bool SP2 = true, bool GS = false>
; __device__ __forceinline__ void gemm_phase(PG8_LAS unsigned char* lds, const Gemm g, const Sched& S, const Epi& E, const float* gs_ss = nullptr) {
;     ...
;         for (int t = 0; t < nt; t += 2) {
;             const bool last = (t == nt - 2);
;             const char* a1 = cA + (size_t)(t + 1) * kstep;
;             const char* a2 = last ? nA : cA + (size_t)(t + 2) * kstep; const char* b2 = last ? nB : cB + (size_t)(t + 2) * kstep;
;             const char* a3 = a2 + kstep; const char* b3 = b2 + kstep;
.LBB0_989:
	s_add_u32 s62, s62, 0x100
	s_addc_u32 s63, s63, 0
	s_cmp_gt_u32 s73, 29
	s_cbranch_scc1 .LBB0_992
	.p2align	6

; template <class Epi, class Sched, bool ALIGN_EPI = true, bool SP2 = true, bool GS = false>
; __device__ __forceinline__ void gemm_phase(PG8_LAS unsigned char* lds, const Gemm g, const Sched& S, const Epi& E, const float* gs_ss = nullptr) {
;     ...
;         for (int t = 0; t < nt; t += 2) {
;             const bool last = (t == nt - 2);
;             const char* a1 = cA + (size_t)(t + 1) * kstep;
;             const char* a2 = last ? nA : cA + (size_t)(t + 2) * kstep; const char* b2 = last ? nB : cB + (size_t)(t + 2) * kstep;
;             const char* a3 = a2 + kstep; const char* b3 = b2 + kstep;
.LBB0_1035:
	s_add_u32 s60, s60, 0x100
	s_addc_u32 s61, s61, 0
	s_cmp_gt_u32 s75, 29
	s_cbranch_scc1 .LBB0_1038
	.p2align	6

;     __device__ __forceinline__ size_t a_extra(const Unit& u) const { return (size_t)(u.pn >> 1) * ((size_t)T * 512 * 2); }
;     __device__ __forceinline__ size_t a_extra(const Unit& u) const { return (size_t)(u.pn >> 1) * 512 * 2; }
;     __device__ __forceinline__ size_t b_extra(const Unit& u) const { return (size_t)(u.pn >> 1) * 512 * 2 - (size_t)(u.pn & ~1) * ((size_t)256 * D * 2); }
; template <class Epi, class Sched, bool ALIGN_EPI = true, bool SP2 = true, bool GS = false>
; __device__ __forceinline__ void gemm_phase(PG8_LAS unsigned char* lds, const Gemm g, const Sched& S, const Epi& E, const float* gs_ss = nullptr) {
;     ...
; #pragma unroll
;         for (int a = 0; a < 2; ++a)
; #pragma unroll
;             for (int b = 0; b < 2; ++b)
; #pragma unroll
;                 for (int m = 0; m < 4; ++m)
; #pragma unroll
;                     for (int n = 0; n < 2; ++n) acc[a][b][m][n] = (f32x4){0.f, 0.f, 0.f, 0.f};
;         cur = nxt; cA = nA; cB = nB; ++ui;
.LBB0_1118:
	s_add_i32 s49, s49, 1
	s_mov_b64 s[2:3], s[28:29]
	s_mov_b32 s28, s8
	s_mov_b32 s51, s8
	s_mul_i32 s8, s49, s66
	s_add_i32 s54, s8, s14
	s_cmpk_lt_i32 s54, 0x100
	s_mov_b32 s29, s24
	s_mov_b32 s50, s24
	s_cselect_b64 s[42:43], -1, 0
	s_and_b32 s24, s54, 7
	s_ashr_i32 s8, s54, 3
	s_mov_b64 s[20:21], s[12:13]
	s_and_b64 s[12:13], s[42:43], exec
	s_cselect_b32 s13, s24, s29
	s_cselect_b32 s12, s8, s28
	s_ashr_i32 s28, s13, 1
	s_ashr_i32 s29, s28, 31
	s_lshl_b64 s[44:45], s[28:29], 10
	s_add_u32 s28, s16, s44
	s_addc_u32 s29, s17, s45
	s_ashr_i32 s13, s12, 31
	s_lshl_b64 s[12:13], s[12:13], 20
	s_add_u32 s28, s28, s12
	s_addc_u32 s29, s29, s13
	s_and_b64 s[12:13], s[42:43], exec
	s_cselect_b32 s52, s29, s3
	s_cselect_b32 s53, s28, s2
	s_lshl_b32 s12, s54, 20
	s_and_b32 s12, s12, 0x600000
	s_sub_u32 s12, s44, s12
	s_subb_u32 s13, s45, 0
	s_add_u32 s12, s18, s12
	s_addc_u32 s13, s22, s13
	s_lshl_b32 s44, s24, 20
	s_add_u32 s12, s12, s44
	s_addc_u32 s13, s13, 0
	s_and_b64 s[44:45], s[42:43], exec
	s_cselect_b32 s54, s13, s21
	s_cselect_b32 s55, s12, s20
	s_add_u32 s44, s2, 0x80080
	s_addc_u32 s45, s3, 0
	s_add_u32 s56, s20, 0x100
	v_mov_b32_e32 v2, 0
	s_addc_u32 s57, s21, 0
	s_mov_b32 s58, -2
	v_mov_b32_e32 v3, v2
	v_mov_b32_e32 v4, v2
	v_mov_b32_e32 v5, v2
	v_mov_b32_e32 v6, v2
	v_mov_b32_e32 v7, v2
	v_mov_b32_e32 v8, v2
	v_mov_b32_e32 v9, v2
	v_mov_b32_e32 v10, v2
	v_mov_b32_e32 v11, v2
	v_mov_b32_e32 v12, v2
	v_mov_b32_e32 v13, v2
	v_mov_b32_e32 v18, v2
	v_mov_b32_e32 v19, v2
	v_mov_b32_e32 v20, v2
	v_mov_b32_e32 v21, v2
	v_mov_b32_e32 v26, v2
	v_mov_b32_e32 v27, v2
	v_mov_b32_e32 v28, v2
	v_mov_b32_e32 v29, v2
	v_mov_b32_e32 v34, v2
	v_mov_b32_e32 v35, v2
	v_mov_b32_e32 v36, v2
	v_mov_b32_e32 v37, v2
	v_mov_b32_e32 v42, v2
	v_mov_b32_e32 v43, v2
	v_mov_b32_e32 v44, v2
	v_mov_b32_e32 v45, v2
	v_mov_b32_e32 v50, v2
	v_mov_b32_e32 v51, v2
	v_mov_b32_e32 v52, v2
	v_mov_b32_e32 v53, v2
	v_mov_b32_e32 v14, v2
	v_mov_b32_e32 v15, v2
	v_mov_b32_e32 v16, v2
	v_mov_b32_e32 v17, v2
	v_mov_b32_e32 v22, v2
	v_mov_b32_e32 v23, v2
	v_mov_b32_e32 v24, v2
	v_mov_b32_e32 v25, v2
	v_mov_b32_e32 v30, v2
	v_mov_b32_e32 v31, v2
	v_mov_b32_e32 v32, v2
	v_mov_b32_e32 v33, v2
	v_mov_b32_e32 v38, v2
	v_mov_b32_e32 v39, v2
	v_mov_b32_e32 v40, v2
	v_mov_b32_e32 v41, v2
	v_mov_b32_e32 v46, v2
	v_mov_b32_e32 v47, v2
	v_mov_b32_e32 v48, v2
	v_mov_b32_e32 v49, v2
	v_mov_b32_e32 v54, v2
	v_mov_b32_e32 v55, v2
	v_mov_b32_e32 v56, v2
	v_mov_b32_e32 v57, v2
	v_mov_b32_e32 v58, v2
	v_mov_b32_e32 v59, v2
	v_mov_b32_e32 v60, v2
	v_mov_b32_e32 v61, v2
	v_mov_b32_e32 v62, v2
	v_mov_b32_e32 v63, v2
	v_mov_b32_e32 v64, v2
	v_mov_b32_e32 v65, v2
	v_mov_b32_e32 v66, v2
	v_mov_b32_e32 v67, v2
	v_mov_b32_e32 v68, v2
	v_mov_b32_e32 v69, v2
	v_mov_b32_e32 v70, v2
	v_mov_b32_e32 v71, v2
	v_mov_b32_e32 v72, v2
	v_mov_b32_e32 v73, v2
	v_mov_b32_e32 v74, v2
	v_mov_b32_e32 v75, v2
	v_mov_b32_e32 v76, v2
	v_mov_b32_e32 v77, v2
	v_mov_b32_e32 v82, v2
	v_mov_b32_e32 v83, v2
	v_mov_b32_e32 v84, v2
	v_mov_b32_e32 v85, v2
	v_mov_b32_e32 v90, v2
	v_mov_b32_e32 v91, v2
	v_mov_b32_e32 v92, v2
	v_mov_b32_e32 v93, v2
	v_mov_b32_e32 v98, v2
	v_mov_b32_e32 v99, v2
	v_mov_b32_e32 v100, v2
	v_mov_b32_e32 v101, v2
	v_mov_b32_e32 v106, v2
	v_mov_b32_e32 v107, v2
	v_mov_b32_e32 v108, v2
	v_mov_b32_e32 v109, v2
	v_mov_b32_e32 v114, v2
	v_mov_b32_e32 v115, v2
	v_mov_b32_e32 v116, v2
	v_mov_b32_e32 v117, v2
	v_mov_b32_e32 v78, v2
	v_mov_b32_e32 v79, v2
	v_mov_b32_e32 v80, v2
	v_mov_b32_e32 v81, v2
	v_mov_b32_e32 v86, v2
	v_mov_b32_e32 v87, v2
	v_mov_b32_e32 v88, v2
	v_mov_b32_e32 v89, v2
	v_mov_b32_e32 v94, v2
	v_mov_b32_e32 v95, v2
	v_mov_b32_e32 v96, v2
	v_mov_b32_e32 v97, v2
	v_mov_b32_e32 v102, v2
	v_mov_b32_e32 v103, v2
	v_mov_b32_e32 v104, v2
	v_mov_b32_e32 v105, v2
	v_mov_b32_e32 v110, v2
	v_mov_b32_e32 v111, v2
	v_mov_b32_e32 v112, v2
	v_mov_b32_e32 v113, v2
	v_mov_b32_e32 v118, v2
	v_mov_b32_e32 v119, v2
	v_mov_b32_e32 v120, v2
	v_mov_b32_e32 v121, v2
	v_mov_b32_e32 v122, v2
	v_mov_b32_e32 v123, v2
	v_mov_b32_e32 v124, v2
	v_mov_b32_e32 v125, v2
	v_mov_b32_e32 v126, v2
	v_mov_b32_e32 v127, v2
	v_mov_b32_e32 v128, v2
	v_mov_b32_e32 v129, v2
	.p2align	6

;     __device__ bool next(int i, Unit& u) const { const int L = i * G + c; if (L >= 192) return false; u.pm = L / 6; u.pn = L % 6; return true; }
;     __device__ __forceinline__ size_t a_extra(const Unit& u) const { return (size_t)(u.pn >> 1) * ((size_t)T * 512 * 2); }
;     __device__ bool next(int i, Unit& u) const { const int L = i * G + c; if (L >= 256) return false; u.pm = L >> 3; u.pn = L & 7; return true; }
;     __device__ __forceinline__ size_t a_extra(const Unit& u) const { return (size_t)(u.pn >> 1) * 512 * 2; }
;     __device__ __forceinline__ size_t b_extra(const Unit& u) const { return (size_t)(u.pn >> 1) * 512 * 2 - (size_t)(u.pn & ~1) * ((size_t)256 * D * 2); }
; template <class Epi, class Sched, bool ALIGN_EPI = true, bool SP2 = true, bool GS = false>
; __device__ __forceinline__ void gemm_phase(PG8_LAS unsigned char* lds, const Gemm g, const Sched& S, const Epi& E, const float* gs_ss = nullptr) {
;     ...
;         const bool has_next = S.next(ui + 1, nxt);
;         const char* nA = has_next ? (const char*)g.A + S.a_extra(nxt) + (size_t)nxt.pm * tstep : cA; const char* nB = has_next ? (const char*)g.Bt + S.b_extra(nxt) + (size_t)nxt.pn * tstep : cB;
;         for (int t = 0; t < nt; t += 2) {
;             const bool last = (t == nt - 2);
;             const char* a1 = cA + (size_t)(t + 1) * kstep;
;             const char* a2 = last ? nA : cA + (size_t)(t + 2) * kstep; const char* b2 = last ? nB : cB + (size_t)(t + 2) * kstep;
;             const char* a3 = a2 + kstep; const char* b3 = b2 + kstep;
;     ...
; #pragma unroll
;         for (int a = 0; a < 2; ++a)
; #pragma unroll
;             for (int b = 0; b < 2; ++b)
; #pragma unroll
;                 for (int m = 0; m < 4; ++m)
; #pragma unroll
;                     for (int n = 0; n < 2; ++n) acc[a][b][m][n] = (f32x4){0.f, 0.f, 0.f, 0.f};
;         cur = nxt; cA = nA; cB = nB; ++ui;
.LBB0_1251:
	s_ashr_i32 s51, s50, 31
	s_lshl_b64 s[2:3], s[50:51], 18
	s_add_u32 s52, s16, s2
	s_addc_u32 s53, s17, s3
	s_and_b64 s[2:3], s[40:41], exec
	s_cselect_b32 s18, s53, s57
	s_cselect_b32 s51, s52, s56
	s_ashr_i32 s49, s48, 31
	s_lshl_b64 s[2:3], s[48:49], 18
	s_add_u32 s54, s22, s2
	s_addc_u32 s55, s23, s3
	s_and_b64 s[2:3], s[40:41], exec
	s_cselect_b32 s49, s55, s59
	s_cselect_b32 s63, s54, s58
	s_add_u32 s56, s56, 0x20080
	s_addc_u32 s57, s57, 0
	s_add_u32 s58, s58, 0x100
	v_mov_b32_e32 v2, 0
	s_addc_u32 s59, s59, 0
	s_mov_b32 s64, -2
	v_mov_b32_e32 v3, v2
	v_mov_b32_e32 v4, v2
	v_mov_b32_e32 v5, v2
	v_mov_b32_e32 v6, v2
	v_mov_b32_e32 v7, v2
	v_mov_b32_e32 v8, v2
	v_mov_b32_e32 v9, v2
	v_mov_b32_e32 v18, v2
	v_mov_b32_e32 v19, v2
	v_mov_b32_e32 v20, v2
	v_mov_b32_e32 v21, v2
	v_mov_b32_e32 v22, v2
	v_mov_b32_e32 v23, v2
	v_mov_b32_e32 v24, v2
	v_mov_b32_e32 v25, v2
	v_mov_b32_e32 v34, v2
	v_mov_b32_e32 v35, v2
	v_mov_b32_e32 v36, v2
	v_mov_b32_e32 v37, v2
	v_mov_b32_e32 v38, v2
	v_mov_b32_e32 v39, v2
	v_mov_b32_e32 v40, v2
	v_mov_b32_e32 v41, v2
	v_mov_b32_e32 v50, v2
	v_mov_b32_e32 v51, v2
	v_mov_b32_e32 v52, v2
	v_mov_b32_e32 v53, v2
	v_mov_b32_e32 v54, v2
	v_mov_b32_e32 v55, v2
	v_mov_b32_e32 v56, v2
	v_mov_b32_e32 v57, v2
	v_mov_b32_e32 v10, v2
	v_mov_b32_e32 v11, v2
	v_mov_b32_e32 v12, v2
	v_mov_b32_e32 v13, v2
	v_mov_b32_e32 v14, v2
	v_mov_b32_e32 v15, v2
	v_mov_b32_e32 v16, v2
	v_mov_b32_e32 v17, v2
	v_mov_b32_e32 v26, v2
	v_mov_b32_e32 v27, v2
	v_mov_b32_e32 v28, v2
	v_mov_b32_e32 v29, v2
	v_mov_b32_e32 v30, v2
	v_mov_b32_e32 v31, v2
	v_mov_b32_e32 v32, v2
	v_mov_b32_e32 v33, v2
	v_mov_b32_e32 v42, v2
	v_mov_b32_e32 v43, v2
	v_mov_b32_e32 v44, v2
	v_mov_b32_e32 v45, v2
	v_mov_b32_e32 v46, v2
	v_mov_b32_e32 v47, v2
	v_mov_b32_e32 v48, v2
	v_mov_b32_e32 v49, v2
	v_mov_b32_e32 v58, v2
	v_mov_b32_e32 v59, v2
	v_mov_b32_e32 v60, v2
	v_mov_b32_e32 v61, v2
	v_mov_b32_e32 v62, v2
	v_mov_b32_e32 v63, v2
	v_mov_b32_e32 v64, v2
	v_mov_b32_e32 v65, v2
	v_mov_b32_e32 v66, v2
	v_mov_b32_e32 v67, v2
	v_mov_b32_e32 v68, v2
	v_mov_b32_e32 v69, v2
	v_mov_b32_e32 v70, v2
	v_mov_b32_e32 v71, v2
	v_mov_b32_e32 v72, v2
	v_mov_b32_e32 v73, v2
	v_mov_b32_e32 v82, v2
	v_mov_b32_e32 v83, v2
	v_mov_b32_e32 v84, v2
	v_mov_b32_e32 v85, v2
	v_mov_b32_e32 v86, v2
	v_mov_b32_e32 v87, v2
	v_mov_b32_e32 v88, v2
	v_mov_b32_e32 v89, v2
	v_mov_b32_e32 v98, v2
	v_mov_b32_e32 v99, v2
	v_mov_b32_e32 v100, v2
	v_mov_b32_e32 v101, v2
	v_mov_b32_e32 v102, v2
	v_mov_b32_e32 v103, v2
	v_mov_b32_e32 v104, v2
	v_mov_b32_e32 v105, v2
	v_mov_b32_e32 v114, v2
	v_mov_b32_e32 v115, v2
	v_mov_b32_e32 v116, v2
	v_mov_b32_e32 v117, v2
	v_mov_b32_e32 v118, v2
	v_mov_b32_e32 v119, v2
	v_mov_b32_e32 v120, v2
	v_mov_b32_e32 v121, v2
	v_mov_b32_e32 v74, v2
	v_mov_b32_e32 v75, v2
	v_mov_b32_e32 v76, v2
	v_mov_b32_e32 v77, v2
	v_mov_b32_e32 v78, v2
	v_mov_b32_e32 v79, v2
	v_mov_b32_e32 v80, v2
	v_mov_b32_e32 v81, v2
	v_mov_b32_e32 v90, v2
	v_mov_b32_e32 v91, v2
	v_mov_b32_e32 v92, v2
	v_mov_b32_e32 v93, v2
	v_mov_b32_e32 v94, v2
	v_mov_b32_e32 v95, v2
	v_mov_b32_e32 v96, v2
	v_mov_b32_e32 v97, v2
	v_mov_b32_e32 v106, v2
	v_mov_b32_e32 v107, v2
	v_mov_b32_e32 v108, v2
	v_mov_b32_e32 v109, v2
	v_mov_b32_e32 v110, v2
	v_mov_b32_e32 v111, v2
	v_mov_b32_e32 v112, v2
	v_mov_b32_e32 v113, v2
	v_mov_b32_e32 v126, v2
	v_mov_b32_e32 v127, v2
	v_mov_b32_e32 v128, v2
	v_mov_b32_e32 v129, v2
	v_mov_b32_e32 v134, v2
	v_mov_b32_e32 v135, v2
	v_mov_b32_e32 v136, v2
	v_mov_b32_e32 v137, v2
	.p2align	6

;     __device__ bool next(int i, Unit& u) const { const int L = i * G + c; if (L >= 192) return false; u.pm = L / 6; u.pn = L % 6; return true; }
;     __device__ __forceinline__ size_t a_extra(const Unit& u) const { return (size_t)(u.pn >> 1) * ((size_t)T * 512 * 2); }
;     __device__ bool next(int i, Unit& u) const { const int L = i * G + c; if (L >= 256) return false; u.pm = L >> 3; u.pn = L & 7; return true; }
;     __device__ __forceinline__ size_t a_extra(const Unit& u) const { return (size_t)(u.pn >> 1) * 512 * 2; }
;     __device__ __forceinline__ size_t b_extra(const Unit& u) const { return (size_t)(u.pn >> 1) * 512 * 2 - (size_t)(u.pn & ~1) * ((size_t)256 * D * 2); }
; template <class Epi, class Sched, bool ALIGN_EPI = true, bool SP2 = true, bool GS = false>
; __device__ __forceinline__ void gemm_phase(PG8_LAS unsigned char* lds, const Gemm g, const Sched& S, const Epi& E, const float* gs_ss = nullptr) {
;     ...
;         const bool has_next = S.next(ui + 1, nxt);
;         const char* nA = has_next ? (const char*)g.A + S.a_extra(nxt) + (size_t)nxt.pm * tstep : cA; const char* nB = has_next ? (const char*)g.Bt + S.b_extra(nxt) + (size_t)nxt.pn * tstep : cB;
;         for (int t = 0; t < nt; t += 2) {
;             const bool last = (t == nt - 2);
;             const char* a1 = cA + (size_t)(t + 1) * kstep;
;             const char* a2 = last ? nA : cA + (size_t)(t + 2) * kstep; const char* b2 = last ? nB : cB + (size_t)(t + 2) * kstep;
;             const char* a3 = a2 + kstep; const char* b3 = b2 + kstep;
;     ...
; #pragma unroll
;         for (int a = 0; a < 2; ++a)
; #pragma unroll
;             for (int b = 0; b < 2; ++b)
; #pragma unroll
;                 for (int m = 0; m < 4; ++m)
; #pragma unroll
;                     for (int n = 0; n < 2; ++n) acc[a][b][m][n] = (f32x4){0.f, 0.f, 0.f, 0.f};
;         cur = nxt; cA = nA; cB = nB; ++ui;
.LBB0_1343:
	s_ashr_i32 s43, s42, 31
	s_lshl_b64 s[2:3], s[42:43], 20
	s_add_u32 s44, s17, s2
	s_addc_u32 s45, s22, s3
	s_and_b64 s[2:3], s[38:39], exec
	s_cselect_b32 s43, s45, s51
	s_cselect_b32 s57, s44, s50
	s_ashr_i32 s41, s40, 31
	s_lshl_b64 s[2:3], s[40:41], 20
	s_add_u32 s46, s23, s2
	s_addc_u32 s47, s24, s3
	s_and_b64 s[2:3], s[38:39], exec
	s_cselect_b32 s41, s47, s53
	s_cselect_b32 s58, s46, s52
	s_add_u32 s50, s50, 0x80080
	s_addc_u32 s51, s51, 0
	s_add_u32 s52, s52, 0x100
	v_mov_b32_e32 v2, 0
	s_addc_u32 s53, s53, 0
	s_mov_b32 s59, -2
	v_mov_b32_e32 v3, v2
	v_mov_b32_e32 v4, v2
	v_mov_b32_e32 v5, v2
	v_mov_b32_e32 v6, v2
	v_mov_b32_e32 v7, v2
	v_mov_b32_e32 v8, v2
	v_mov_b32_e32 v9, v2
	v_mov_b32_e32 v18, v2
	v_mov_b32_e32 v19, v2
	v_mov_b32_e32 v20, v2
	v_mov_b32_e32 v21, v2
	v_mov_b32_e32 v22, v2
	v_mov_b32_e32 v23, v2
	v_mov_b32_e32 v24, v2
	v_mov_b32_e32 v25, v2
	v_mov_b32_e32 v34, v2
	v_mov_b32_e32 v35, v2
	v_mov_b32_e32 v36, v2
	v_mov_b32_e32 v37, v2
	v_mov_b32_e32 v38, v2
	v_mov_b32_e32 v39, v2
	v_mov_b32_e32 v40, v2
	v_mov_b32_e32 v41, v2
	v_mov_b32_e32 v50, v2
	v_mov_b32_e32 v51, v2
	v_mov_b32_e32 v52, v2
	v_mov_b32_e32 v53, v2
	v_mov_b32_e32 v54, v2
	v_mov_b32_e32 v55, v2
	v_mov_b32_e32 v56, v2
	v_mov_b32_e32 v57, v2
	v_mov_b32_e32 v10, v2
	v_mov_b32_e32 v11, v2
	v_mov_b32_e32 v12, v2
	v_mov_b32_e32 v13, v2
	v_mov_b32_e32 v14, v2
	v_mov_b32_e32 v15, v2
	v_mov_b32_e32 v16, v2
	v_mov_b32_e32 v17, v2
	v_mov_b32_e32 v26, v2
	v_mov_b32_e32 v27, v2
	v_mov_b32_e32 v28, v2
	v_mov_b32_e32 v29, v2
	v_mov_b32_e32 v30, v2
	v_mov_b32_e32 v31, v2
	v_mov_b32_e32 v32, v2
	v_mov_b32_e32 v33, v2
	v_mov_b32_e32 v42, v2
	v_mov_b32_e32 v43, v2
	v_mov_b32_e32 v44, v2
	v_mov_b32_e32 v45, v2
	v_mov_b32_e32 v46, v2
	v_mov_b32_e32 v47, v2
	v_mov_b32_e32 v48, v2
	v_mov_b32_e32 v49, v2
	v_mov_b32_e32 v58, v2
	v_mov_b32_e32 v59, v2
	v_mov_b32_e32 v60, v2
	v_mov_b32_e32 v61, v2
	v_mov_b32_e32 v62, v2
	v_mov_b32_e32 v63, v2
	v_mov_b32_e32 v64, v2
	v_mov_b32_e32 v65, v2
	v_mov_b32_e32 v66, v2
	v_mov_b32_e32 v67, v2
	v_mov_b32_e32 v68, v2
	v_mov_b32_e32 v69, v2
	v_mov_b32_e32 v70, v2
	v_mov_b32_e32 v71, v2
	v_mov_b32_e32 v72, v2
	v_mov_b32_e32 v73, v2
	v_mov_b32_e32 v82, v2
	v_mov_b32_e32 v83, v2
	v_mov_b32_e32 v84, v2
	v_mov_b32_e32 v85, v2
	v_mov_b32_e32 v86, v2
	v_mov_b32_e32 v87, v2
	v_mov_b32_e32 v88, v2
	v_mov_b32_e32 v89, v2
	v_mov_b32_e32 v98, v2
	v_mov_b32_e32 v99, v2
	v_mov_b32_e32 v100, v2
	v_mov_b32_e32 v101, v2
	v_mov_b32_e32 v102, v2
	v_mov_b32_e32 v103, v2
	v_mov_b32_e32 v104, v2
	v_mov_b32_e32 v105, v2
	v_mov_b32_e32 v114, v2
	v_mov_b32_e32 v115, v2
	v_mov_b32_e32 v116, v2
	v_mov_b32_e32 v117, v2
	v_mov_b32_e32 v118, v2
	v_mov_b32_e32 v119, v2
	v_mov_b32_e32 v120, v2
	v_mov_b32_e32 v121, v2
	v_mov_b32_e32 v74, v2
	v_mov_b32_e32 v75, v2
	v_mov_b32_e32 v76, v2
	v_mov_b32_e32 v77, v2
	v_mov_b32_e32 v78, v2
	v_mov_b32_e32 v79, v2
	v_mov_b32_e32 v80, v2
	v_mov_b32_e32 v81, v2
	v_mov_b32_e32 v90, v2
	v_mov_b32_e32 v91, v2
	v_mov_b32_e32 v92, v2
	v_mov_b32_e32 v93, v2
	v_mov_b32_e32 v94, v2
	v_mov_b32_e32 v95, v2
	v_mov_b32_e32 v96, v2
	v_mov_b32_e32 v97, v2
	v_mov_b32_e32 v106, v2
	v_mov_b32_e32 v107, v2
	v_mov_b32_e32 v108, v2
	v_mov_b32_e32 v109, v2
	v_mov_b32_e32 v110, v2
	v_mov_b32_e32 v111, v2
	v_mov_b32_e32 v112, v2
	v_mov_b32_e32 v113, v2
	v_mov_b32_e32 v122, v2
	v_mov_b32_e32 v123, v2
	v_mov_b32_e32 v124, v2
	v_mov_b32_e32 v125, v2
	v_mov_b32_e32 v126, v2
	v_mov_b32_e32 v127, v2
	v_mov_b32_e32 v128, v2
	v_mov_b32_e32 v129, v2
	.p2align	6

;     __device__ bool next(int i, Unit& u) const { const int L = i * G + c; if (L >= 192) return false; u.pm = L / 6; u.pn = L % 6; return true; }
;     __device__ __forceinline__ size_t a_extra(const Unit& u) const { return (size_t)(u.pn >> 1) * ((size_t)T * 512 * 2); }
;     __device__ bool next(int i, Unit& u) const { const int L = i * G + c; if (L >= 256) return false; u.pm = L >> 3; u.pn = L & 7; return true; }
;     __device__ __forceinline__ size_t a_extra(const Unit& u) const { return (size_t)(u.pn >> 1) * 512 * 2; }
;     __device__ __forceinline__ size_t b_extra(const Unit& u) const { return (size_t)(u.pn >> 1) * 512 * 2 - (size_t)(u.pn & ~1) * ((size_t)256 * D * 2); }
; template <class Epi, class Sched, bool ALIGN_EPI = true, bool SP2 = true, bool GS = false>
; __device__ __forceinline__ void gemm_phase(PG8_LAS unsigned char* lds, const Gemm g, const Sched& S, const Epi& E, const float* gs_ss = nullptr) {
;     ...
;         const bool has_next = S.next(ui + 1, nxt);
;         const char* nA = has_next ? (const char*)g.A + S.a_extra(nxt) + (size_t)nxt.pm * tstep : cA; const char* nB = has_next ? (const char*)g.Bt + S.b_extra(nxt) + (size_t)nxt.pn * tstep : cB;
;         for (int t = 0; t < nt; t += 2) {
;             const bool last = (t == nt - 2);
;             const char* a1 = cA + (size_t)(t + 1) * kstep;
;             const char* a2 = last ? nA : cA + (size_t)(t + 2) * kstep; const char* b2 = last ? nB : cB + (size_t)(t + 2) * kstep;
;             const char* a3 = a2 + kstep; const char* b3 = b2 + kstep;
;     ...
; #pragma unroll
;         for (int a = 0; a < 2; ++a)
; #pragma unroll
;             for (int b = 0; b < 2; ++b)
; #pragma unroll
;                 for (int m = 0; m < 4; ++m)
; #pragma unroll
;                     for (int n = 0; n < 2; ++n) acc[a][b][m][n] = (f32x4){0.f, 0.f, 0.f, 0.f};
;         cur = nxt; cA = nA; cB = nB; ++ui;
.LBB0_1421:
	s_ashr_i32 s51, s50, 31
	s_lshl_b64 s[2:3], s[50:51], 22
	s_add_u32 s52, s16, s2
	s_addc_u32 s53, s17, s3
	s_and_b64 s[2:3], s[40:41], exec
	s_cselect_b32 s18, s53, s57
	s_cselect_b32 s51, s52, s56
	s_ashr_i32 s49, s48, 31
	s_lshl_b64 s[2:3], s[48:49], 22
	s_add_u32 s54, s22, s2
	s_addc_u32 s55, s23, s3
	s_and_b64 s[2:3], s[40:41], exec
	s_cselect_b32 s49, s55, s59
	s_cselect_b32 s63, s54, s58
	s_add_u32 s56, s56, 0x200080
	s_addc_u32 s57, s57, 0
	s_add_u32 s58, s58, 0x100
	v_mov_b32_e32 v2, 0
	s_addc_u32 s59, s59, 0
	s_mov_b32 s64, -2
	v_mov_b32_e32 v3, v2
	v_mov_b32_e32 v4, v2
	v_mov_b32_e32 v5, v2
	v_mov_b32_e32 v6, v2
	v_mov_b32_e32 v7, v2
	v_mov_b32_e32 v8, v2
	v_mov_b32_e32 v9, v2
	v_mov_b32_e32 v18, v2
	v_mov_b32_e32 v19, v2
	v_mov_b32_e32 v20, v2
	v_mov_b32_e32 v21, v2
	v_mov_b32_e32 v22, v2
	v_mov_b32_e32 v23, v2
	v_mov_b32_e32 v24, v2
	v_mov_b32_e32 v25, v2
	v_mov_b32_e32 v34, v2
	v_mov_b32_e32 v35, v2
	v_mov_b32_e32 v36, v2
	v_mov_b32_e32 v37, v2
	v_mov_b32_e32 v38, v2
	v_mov_b32_e32 v39, v2
	v_mov_b32_e32 v40, v2
	v_mov_b32_e32 v41, v2
	v_mov_b32_e32 v50, v2
	v_mov_b32_e32 v51, v2
	v_mov_b32_e32 v52, v2
	v_mov_b32_e32 v53, v2
	v_mov_b32_e32 v54, v2
	v_mov_b32_e32 v55, v2
	v_mov_b32_e32 v56, v2
	v_mov_b32_e32 v57, v2
	v_mov_b32_e32 v10, v2
	v_mov_b32_e32 v11, v2
	v_mov_b32_e32 v12, v2
	v_mov_b32_e32 v13, v2
	v_mov_b32_e32 v14, v2
	v_mov_b32_e32 v15, v2
	v_mov_b32_e32 v16, v2
	v_mov_b32_e32 v17, v2
	v_mov_b32_e32 v26, v2
	v_mov_b32_e32 v27, v2
	v_mov_b32_e32 v28, v2
	v_mov_b32_e32 v29, v2
	v_mov_b32_e32 v30, v2
	v_mov_b32_e32 v31, v2
	v_mov_b32_e32 v32, v2
	v_mov_b32_e32 v33, v2
	v_mov_b32_e32 v42, v2
	v_mov_b32_e32 v43, v2
	v_mov_b32_e32 v44, v2
	v_mov_b32_e32 v45, v2
	v_mov_b32_e32 v46, v2
	v_mov_b32_e32 v47, v2
	v_mov_b32_e32 v48, v2
	v_mov_b32_e32 v49, v2
	v_mov_b32_e32 v58, v2
	v_mov_b32_e32 v59, v2
	v_mov_b32_e32 v60, v2
	v_mov_b32_e32 v61, v2
	v_mov_b32_e32 v62, v2
	v_mov_b32_e32 v63, v2
	v_mov_b32_e32 v64, v2
	v_mov_b32_e32 v65, v2
	v_mov_b32_e32 v66, v2
	v_mov_b32_e32 v67, v2
	v_mov_b32_e32 v68, v2
	v_mov_b32_e32 v69, v2
	v_mov_b32_e32 v70, v2
	v_mov_b32_e32 v71, v2
	v_mov_b32_e32 v72, v2
	v_mov_b32_e32 v73, v2
	v_mov_b32_e32 v82, v2
	v_mov_b32_e32 v83, v2
	v_mov_b32_e32 v84, v2
	v_mov_b32_e32 v85, v2
	v_mov_b32_e32 v86, v2
	v_mov_b32_e32 v87, v2
	v_mov_b32_e32 v88, v2
	v_mov_b32_e32 v89, v2
	v_mov_b32_e32 v98, v2
	v_mov_b32_e32 v99, v2
	v_mov_b32_e32 v100, v2
	v_mov_b32_e32 v101, v2
	v_mov_b32_e32 v102, v2
	v_mov_b32_e32 v103, v2
	v_mov_b32_e32 v104, v2
	v_mov_b32_e32 v105, v2
	v_mov_b32_e32 v114, v2
	v_mov_b32_e32 v115, v2
	v_mov_b32_e32 v116, v2
	v_mov_b32_e32 v117, v2
	v_mov_b32_e32 v118, v2
	v_mov_b32_e32 v119, v2
	v_mov_b32_e32 v120, v2
	v_mov_b32_e32 v121, v2
	v_mov_b32_e32 v74, v2
	v_mov_b32_e32 v75, v2
	v_mov_b32_e32 v76, v2
	v_mov_b32_e32 v77, v2
	v_mov_b32_e32 v78, v2
	v_mov_b32_e32 v79, v2
	v_mov_b32_e32 v80, v2
	v_mov_b32_e32 v81, v2
	v_mov_b32_e32 v90, v2
	v_mov_b32_e32 v91, v2
	v_mov_b32_e32 v92, v2
	v_mov_b32_e32 v93, v2
	v_mov_b32_e32 v94, v2
	v_mov_b32_e32 v95, v2
	v_mov_b32_e32 v96, v2
	v_mov_b32_e32 v97, v2
	v_mov_b32_e32 v106, v2
	v_mov_b32_e32 v107, v2
	v_mov_b32_e32 v108, v2
	v_mov_b32_e32 v109, v2
	v_mov_b32_e32 v110, v2
	v_mov_b32_e32 v111, v2
	v_mov_b32_e32 v112, v2
	v_mov_b32_e32 v113, v2
	v_mov_b32_e32 v122, v2
	v_mov_b32_e32 v123, v2
	v_mov_b32_e32 v124, v2
	v_mov_b32_e32 v125, v2
	v_mov_b32_e32 v126, v2
	v_mov_b32_e32 v127, v2
	v_mov_b32_e32 v128, v2
	v_mov_b32_e32 v129, v2
	.p2align	6
